# P5: next unit's LN-stat loads hoisted to the loop top (land under the LayerNorm phase) instead of load+wait right after the barrier
# baseline (speedup 1.0000x reference)
; __device__ __forceinline__ bf16x8 tobf8(f32x8 x) { u32x4 w = {cvtpk(x[0], x[1]), cvtpk(x[2], x[3]), cvtpk(x[4], x[5]), cvtpk(x[6], x[7])}; return *reinterpret_cast<bf16x8*>(&w); }
; __device__ __forceinline__ void spatial_phase(const Params& p, char* lds) {
;     ...
;         if (g != g_loaded) { g_loaded = g;
; #pragma unroll
;             for (int st_ = 0; st_ < 2; ++st_)
; #pragma unroll
;                 for (int ks = 0; ks < 4; ++ks) { const int s0 = 64 * st_ + 16 * ks + 8 * hi; const float* wp = p.w_sp + ((size_t)g * CCH + t) * CCH + s0;
;                     const f32x4 a = *(const f32x4*)wp, c = *(const f32x4*)(wp + 4); f32x8 y;
; #pragma unroll
;                     for (int i = 0; i < 4; ++i) { y[i] = (s0 + i <= t) ? a[i] : 0.f; y[4 + i] = (s0 + 4 + i <= t) ? c[i] : 0.f; }
;                     pa[st_][ks] = tobf8(y); }
.LBB0_1202:
	s_lshl_b32 s74, s42, 10
	v_lshl_add_u64 v[22:23], v[220:221], 0, s[74:75]
	v_lshl_add_u64 v[24:25], v[222:223], 0, s[74:75]
	global_load_dwordx4 v[32:35], v[22:23], off
	global_load_dwordx4 v[36:39], v[22:23], off offset:16
	global_load_dwordx4 v[48:51], v[22:23], off offset:512
	global_load_dwordx4 v[52:55], v[22:23], off offset:528
	global_load_dwordx4 v[40:43], v[24:25], off
	global_load_dwordx4 v[44:47], v[24:25], off offset:16
	global_load_dwordx4 v[56:59], v[24:25], off offset:512
	global_load_dwordx4 v[60:63], v[24:25], off offset:528
	s_waitcnt vmcnt(0)
	v_readlane_b32 s98, v253, 9
	s_add_i32 s98, s79, s98
	s_cmpk_gt_i32 s98, 0x5ff
	s_cbranch_scc1 .Lp5h_skip
	s_cmpk_lt_i32 s98, 0x400
	s_cbranch_scc0 .Lp5h_samp
	s_ashr_i32 s98, s98, 4
	s_lshl_b32 s98, s98, 7
	s_branch .Lp5h_j
.Lp5h_samp:
	s_and_b32 s98, s98, 0x7ffffff0
	s_addk_i32 s98, 0x1c00
.Lp5h_j:
	s_lshl_b32 s98, s98, 2
	s_add_u32 s98, s98, s92
	s_addc_u32 s99, s93, 0
	v_lshlrev_b32_e32 v244, 2, v180
	v_mov_b32_e32 v245, 0
	v_lshl_add_u64 v[244:245], s[98:99], 0, v[244:245]
	s_mov_b32 s100, 0x10000
	s_mov_b32 s101, 0
	v_lshl_add_u64 v[244:245], v[244:245], 0, s[100:101]
	global_load_dword v236, v[244:245], off
	global_load_dword v237, v[244:245], off offset:128
	global_load_dword v238, v[244:245], off offset:256
	global_load_dword v239, v[244:245], off offset:384
	v_lshl_add_u64 v[244:245], v[244:245], 0, s[100:101]
	global_load_dword v240, v[244:245], off
	global_load_dword v241, v[244:245], off offset:128
	global_load_dword v242, v[244:245], off offset:256
	global_load_dword v243, v[244:245], off offset:384

.LBB0_1238:
	s_and_b32 s40, s79, 15
	s_mulk_i32 s40, 0x2200
	s_add_u32 s76, s58, s40
	s_addc_u32 s77, s59, 0
	v_mov_b32_e32 v97, v96
	v_mov_b32_e32 v98, v96
	v_mov_b32_e32 v99, v96
	v_lshl_add_u64 v[0:1], s[76:77], 0, v[180:181]
	s_lshl_b64 s[98:99], s[58:59], 2
	s_add_u32 s98, s98, s92
	s_addc_u32 s99, s99, s93
	s_mov_b32 s100, 0x10000
	s_mov_b32 s101, 0
	v_lshlrev_b32_e32 v22, 2, v180
	v_mov_b32_e32 v23, 0
	v_lshl_add_u64 v[22:23], s[98:99], 0, v[22:23]
	v_lshl_add_u64 v[22:23], v[22:23], 0, s[100:101]
	v_lshl_add_u64 v[22:23], v[22:23], 0, s[100:101]
	s_waitcnt vmcnt(0)
	v_mov_b32_e32 v24, v236
	v_mov_b32_e32 v25, v237
	v_mov_b32_e32 v26, v238
	v_mov_b32_e32 v27, v239
	v_mov_b32_e32 v28, v240
	v_mov_b32_e32 v29, v241
	v_mov_b32_e32 v30, v242
	v_mov_b32_e32 v31, v243
	v_mov_b64_e32 v[64:65], v[96:97]
	v_cmp_gt_u32_e32 vcc, s81, v180
	v_lshlrev_b64 v[0:1], 9, v[0:1]
	v_mov_b64_e32 v[66:67], v[98:99]
	s_and_saveexec_b64 s[40:41], vcc
	s_cbranch_execz .LBB0_1240
	v_lshl_add_u64 v[2:3], v[192:193], 0, v[0:1]
	global_load_dwordx4 v[64:67], v[2:3], off nt
